# EpiResid0 GEMM: touch base tile 4 K-iterations before the epilogue; p->bf16 4 loads in flight; HGRN mode1 next-chunk touches
# speedup vs baseline: 1.0133x; 1.0012x over previous
; #define LAS __attribute__((address_space(3)))
; __device__ __forceinline__ float bf2f(unsigned short h) { return __uint_as_float(((unsigned)h) << 16); }
; __device__ __forceinline__ float sigmoidf_(float x) { return __builtin_amdgcn_rcpf(1.f + __expf(-x)); }
; template <int MODE> __device__ __forceinline__ void hgrn_unit(LAS unsigned char* lds, const Params& P, int unit) {
;     ...
;     for (int c = 0; c < 4; ++c) {
;         const int t0 = tok0 + 64 * c;
; #pragma unroll
;         for (int i = 0; i < 2; ++i) { const int ch = tid + 512 * i, r = ch >> 4, cc = ch & 15;
;             *(LAS u32x4*)(T3 + r * TS + cc * 16) = *(const u32x4*)(ZA + (size_t)(t0 + r) * 4096 + 2048 + h * 128 + cc * 8); }
;         float bb[16], kk[16], qq[16];
;         float run = 0.f;
; #pragma unroll
;         for (int i = 0; i < 16; ++i) {
;             const size_t ro = (size_t)(t0 + 16 * g + i) * 4096 + h * 128 + k;
;             const float x = bf2f(ZA[ro + 1024]);
;             const float f = lb + (1.f - lb) * sigmoidf_(x);
;             run += __logf(f); bb[i] = run; kk[i] = 1.f - f;
;             if (MODE == 1) qq[i] = bf2f(ZA[ro]);
;         }
.LBB0_225:
	v_add_u32_e32 v32, s11, v86
	v_ashrrev_i32_e32 v33, 31, v32
	v_lshlrev_b64 v[32:33], 13, v[32:33]
	v_lshl_add_u64 v[32:33], s[72:73], 0, v[32:33]
	s_lshl_b32 s22, s5, 1
	v_lshl_add_u64 v[32:33], v[32:33], 0, s[22:23]
	v_lshl_add_u64 v[32:33], v[32:33], 0, v[180:181]
	v_add_co_u32_e32 v32, vcc, s78, v32
	s_nop 1
	v_addc_co_u32_e32 v33, vcc, 0, v33, vcc
	v_add_co_u32_e32 v170, vcc, 0x80000, v32
	s_nop 1
	v_addc_co_u32_e32 v171, vcc, 0, v33, vcc
	global_load_dwordx4 v[190:193], v[32:33], off
	v_add_u32_e32 v32, s11, v85
	v_ashrrev_i32_e32 v33, 31, v32
	v_lshlrev_b64 v[32:33], 13, v[32:33]
	v_lshl_add_u64 v[32:33], s[72:73], 0, v[32:33]
	v_lshl_add_u64 v[32:33], v[32:33], 0, s[22:23]
	v_lshl_add_u64 v[32:33], v[32:33], 0, v[180:181]
	v_add_co_u32_e32 v32, vcc, s78, v32
	s_nop 1
	v_addc_co_u32_e32 v33, vcc, 0, v33, vcc
	v_add_co_u32_e32 v160, vcc, 0x80000, v32
	s_nop 1
	v_addc_co_u32_e32 v161, vcc, 0, v33, vcc
	global_load_dwordx4 v[194:197], v[32:33], off
	v_add_u32_e32 v32, s11, v84
	v_add_u32_e32 v34, 0, v32
	v_ashrrev_i32_e32 v35, 31, v34
	v_lshlrev_b64 v[34:35], 13, v[34:35]
	v_lshl_add_u64 v[34:35], v[48:49], 0, v[34:35]
	global_load_ushort v172, v[34:35], off offset:2048
	global_load_ushort v38, v[34:35], off
	v_add_u32_e32 v34, 1, v32
	v_ashrrev_i32_e32 v35, 31, v34
	v_lshlrev_b64 v[34:35], 13, v[34:35]
	v_lshl_add_u64 v[34:35], v[48:49], 0, v[34:35]
	global_load_ushort v173, v[34:35], off offset:2048
	global_load_ushort v41, v[34:35], off
	v_add_u32_e32 v34, 2, v32
	v_ashrrev_i32_e32 v35, 31, v34
	v_lshlrev_b64 v[34:35], 13, v[34:35]
	v_lshl_add_u64 v[34:35], v[48:49], 0, v[34:35]
	global_load_ushort v174, v[34:35], off offset:2048
	global_load_ushort v44, v[34:35], off
	v_add_u32_e32 v34, 3, v32
	v_ashrrev_i32_e32 v35, 31, v34
	v_lshlrev_b64 v[34:35], 13, v[34:35]
	v_lshl_add_u64 v[34:35], v[48:49], 0, v[34:35]
	global_load_ushort v175, v[34:35], off offset:2048
	global_load_ushort v47, v[34:35], off
	v_add_u32_e32 v34, 4, v32
	v_ashrrev_i32_e32 v35, 31, v34
	v_lshlrev_b64 v[34:35], 13, v[34:35]
	v_lshl_add_u64 v[34:35], v[48:49], 0, v[34:35]
	global_load_ushort v176, v[34:35], off offset:2048
	global_load_ushort v106, v[34:35], off
	v_add_u32_e32 v34, 5, v32
	v_ashrrev_i32_e32 v35, 31, v34
	v_lshlrev_b64 v[34:35], 13, v[34:35]
	v_lshl_add_u64 v[34:35], v[48:49], 0, v[34:35]
	global_load_ushort v177, v[34:35], off offset:2048
	global_load_ushort v109, v[34:35], off
	v_add_u32_e32 v34, 6, v32
	v_ashrrev_i32_e32 v35, 31, v34
	v_lshlrev_b64 v[34:35], 13, v[34:35]
	v_lshl_add_u64 v[34:35], v[48:49], 0, v[34:35]
	global_load_ushort v178, v[34:35], off offset:2048
	global_load_ushort v112, v[34:35], off
	v_add_u32_e32 v34, 7, v32
	v_ashrrev_i32_e32 v35, 31, v34
	v_lshlrev_b64 v[34:35], 13, v[34:35]
	v_lshl_add_u64 v[34:35], v[48:49], 0, v[34:35]
	global_load_ushort v179, v[34:35], off offset:2048
	global_load_ushort v115, v[34:35], off
	v_add_u32_e32 v34, 8, v32
	v_ashrrev_i32_e32 v35, 31, v34
	v_lshlrev_b64 v[34:35], 13, v[34:35]
	v_lshl_add_u64 v[34:35], v[48:49], 0, v[34:35]
	global_load_ushort v182, v[34:35], off offset:2048
	global_load_ushort v118, v[34:35], off
	v_add_u32_e32 v34, 9, v32
	v_ashrrev_i32_e32 v35, 31, v34
	v_lshlrev_b64 v[34:35], 13, v[34:35]
	v_lshl_add_u64 v[34:35], v[48:49], 0, v[34:35]
	global_load_ushort v183, v[34:35], off offset:2048
	global_load_ushort v121, v[34:35], off
	v_add_u32_e32 v34, 10, v32
	v_ashrrev_i32_e32 v35, 31, v34
	v_lshlrev_b64 v[34:35], 13, v[34:35]
	v_lshl_add_u64 v[34:35], v[48:49], 0, v[34:35]
	global_load_ushort v184, v[34:35], off offset:2048
	global_load_ushort v124, v[34:35], off
	v_add_u32_e32 v34, 11, v32
	v_ashrrev_i32_e32 v35, 31, v34
	v_lshlrev_b64 v[34:35], 13, v[34:35]
	v_lshl_add_u64 v[34:35], v[48:49], 0, v[34:35]
	global_load_ushort v185, v[34:35], off offset:2048
	global_load_ushort v127, v[34:35], off
	v_add_u32_e32 v34, 12, v32
	v_ashrrev_i32_e32 v35, 31, v34
	v_lshlrev_b64 v[34:35], 13, v[34:35]
	v_lshl_add_u64 v[34:35], v[48:49], 0, v[34:35]
	global_load_ushort v186, v[34:35], off offset:2048
	global_load_ushort v130, v[34:35], off
	v_add_u32_e32 v34, 13, v32
	v_ashrrev_i32_e32 v35, 31, v34
	v_lshlrev_b64 v[34:35], 13, v[34:35]
	v_lshl_add_u64 v[34:35], v[48:49], 0, v[34:35]
	global_load_ushort v187, v[34:35], off offset:2048
	global_load_ushort v133, v[34:35], off
	v_add_u32_e32 v34, 14, v32
	v_ashrrev_i32_e32 v35, 31, v34
	v_lshlrev_b64 v[34:35], 13, v[34:35]
	v_lshl_add_u64 v[34:35], v[48:49], 0, v[34:35]
	global_load_ushort v188, v[34:35], off offset:2048
	global_load_ushort v139, v[34:35], off
	v_add_u32_e32 v34, 15, v32
	v_ashrrev_i32_e32 v35, 31, v34
	v_lshlrev_b64 v[34:35], 13, v[34:35]
	v_lshl_add_u64 v[34:35], v[48:49], 0, v[34:35]
	global_load_ushort v189, v[34:35], off offset:2048
	global_load_ushort v153, v[34:35], off
	v_and_b32_e32 v168, 15, v208
	v_add3_u32 v168, v32, v168, 64
	v_ashrrev_i32_e32 v169, 31, v168
	v_lshlrev_b64 v[168:169], 13, v[168:169]
	v_lshl_add_u64 v[168:169], v[48:49], 0, v[168:169]
	global_load_ushort v164, v[168:169], off offset:2048
	global_load_ushort v165, v[168:169], off
	global_load_dword v166, v[170:171], off
	global_load_dword v167, v[160:161], off
	s_waitcnt vmcnt(37)
	ds_write_b128 v87, v[190:193] offset:36864
	s_waitcnt vmcnt(36)
	ds_write_b128 v88, v[194:197] offset:36864
	s_waitcnt vmcnt(35)
; __device__ __forceinline__ float bf2f(unsigned short h) { return __uint_as_float(((unsigned)h) << 16); }
; __device__ __forceinline__ float sigmoidf_(float x) { return __builtin_amdgcn_rcpf(1.f + __expf(-x)); }
; template <int MODE> __device__ __forceinline__ void hgrn_unit(LAS unsigned char* lds, const Params& P, int unit) {
;     ...
; #pragma unroll
;         for (int i = 0; i < 16; ++i) {
;             const size_t ro = (size_t)(t0 + 16 * g + i) * 4096 + h * 128 + k;
;             const float x = bf2f(ZA[ro + 1024]);
;             const float f = lb + (1.f - lb) * sigmoidf_(x);
;             run += __logf(f); bb[i] = run; kk[i] = 1.f - f;
;             if (MODE == 1) qq[i] = bf2f(ZA[ro]);
;         }
	v_lshlrev_b32_e32 v33, 16, v172
	v_mul_f32_e32 v33, 0xbfb8aa3b, v33
	v_exp_f32_e32 v33, v33
	s_nop 0
	v_add_f32_e32 v33, 1.0, v33
	v_rcp_f32_e32 v33, v33
	s_nop 0
	v_fma_f32 v37, v71, v33, v70
	v_cmp_gt_f32_e32 vcc, s71, v37
	s_nop 1
	v_cndmask_b32_e64 v33, 0, 32, vcc
	v_ldexp_f32 v33, v37, v33
	v_log_f32_e32 v33, v33
	s_nop 0
	v_mul_f32_e32 v36, 0x3f317217, v33
	v_fma_f32 v36, v33, s95, -v36
	v_fmac_f32_e32 v36, 0x3377d1cf, v33
	v_fmac_f32_e32 v36, 0x3f317217, v33
	v_cmp_lt_f32_e64 s[0:1], |v33|, s88
	s_nop 1
	v_cndmask_b32_e64 v33, v33, v36, s[0:1]
	v_cndmask_b32_e32 v36, 0, v213, vcc
	v_sub_f32_e32 v33, v33, v36
	v_add_f32_e32 v36, 0, v33
	s_waitcnt vmcnt(33)
	v_lshlrev_b32_e32 v33, 16, v173
	v_mul_f32_e32 v33, 0xbfb8aa3b, v33
	v_exp_f32_e32 v33, v33
	s_nop 0
	v_add_f32_e32 v33, 1.0, v33
	v_rcp_f32_e32 v33, v33
	s_nop 0
	v_fma_f32 v40, v71, v33, v70
	v_cmp_gt_f32_e32 vcc, s71, v40
	s_nop 1
	v_cndmask_b32_e64 v33, 0, 32, vcc
	v_ldexp_f32 v33, v40, v33
	v_log_f32_e32 v33, v33
	s_nop 0
	v_mul_f32_e32 v39, 0x3f317217, v33
	v_fma_f32 v39, v33, s95, -v39
	v_fmac_f32_e32 v39, 0x3377d1cf, v33
	v_fmac_f32_e32 v39, 0x3f317217, v33
	v_cmp_lt_f32_e64 s[0:1], |v33|, s88
	s_nop 1
	v_cndmask_b32_e64 v33, v33, v39, s[0:1]
	v_cndmask_b32_e32 v39, 0, v213, vcc
	v_sub_f32_e32 v33, v33, v39
	v_add_f32_e32 v39, v36, v33
	s_waitcnt vmcnt(31)
	v_lshlrev_b32_e32 v33, 16, v174
	v_mul_f32_e32 v33, 0xbfb8aa3b, v33
	v_exp_f32_e32 v33, v33
	s_nop 0
	v_add_f32_e32 v33, 1.0, v33
	v_rcp_f32_e32 v33, v33
	s_nop 0
	v_fma_f32 v43, v71, v33, v70
	v_cmp_gt_f32_e32 vcc, s71, v43
	s_nop 1
	v_cndmask_b32_e64 v33, 0, 32, vcc
	v_ldexp_f32 v33, v43, v33
	v_log_f32_e32 v33, v33
	s_nop 0
	v_mul_f32_e32 v42, 0x3f317217, v33
	v_fma_f32 v42, v33, s95, -v42
	v_fmac_f32_e32 v42, 0x3377d1cf, v33
	v_fmac_f32_e32 v42, 0x3f317217, v33
	v_cmp_lt_f32_e64 s[0:1], |v33|, s88
	s_nop 1
	v_cndmask_b32_e64 v33, v33, v42, s[0:1]
	v_cndmask_b32_e32 v42, 0, v213, vcc
	v_sub_f32_e32 v33, v33, v42
	v_add_f32_e32 v42, v39, v33
	s_waitcnt vmcnt(29)
	v_lshlrev_b32_e32 v33, 16, v175
	v_mul_f32_e32 v33, 0xbfb8aa3b, v33
	v_exp_f32_e32 v33, v33
	s_nop 0
	v_add_f32_e32 v33, 1.0, v33
	v_rcp_f32_e32 v33, v33
	s_nop 0
	v_fma_f32 v46, v71, v33, v70
	v_cmp_gt_f32_e32 vcc, s71, v46
	s_nop 1
	v_cndmask_b32_e64 v33, 0, 32, vcc
	v_ldexp_f32 v33, v46, v33
	v_log_f32_e32 v33, v33
	s_nop 0
	v_mul_f32_e32 v45, 0x3f317217, v33
	v_fma_f32 v45, v33, s95, -v45
	v_fmac_f32_e32 v45, 0x3377d1cf, v33
	v_fmac_f32_e32 v45, 0x3f317217, v33
	v_cmp_lt_f32_e64 s[0:1], |v33|, s88
	s_nop 1
	v_cndmask_b32_e64 v33, v33, v45, s[0:1]
	v_cndmask_b32_e32 v45, 0, v213, vcc
	v_sub_f32_e32 v33, v33, v45
	v_add_f32_e32 v45, v42, v33
	s_waitcnt vmcnt(27)
	v_lshlrev_b32_e32 v33, 16, v176
	v_mul_f32_e32 v33, 0xbfb8aa3b, v33
	v_exp_f32_e32 v33, v33
	s_nop 0
	v_add_f32_e32 v33, 1.0, v33
	v_rcp_f32_e32 v33, v33
	s_nop 0
	v_fma_f32 v67, v71, v33, v70
	v_cmp_gt_f32_e32 vcc, s71, v67
	s_nop 1
	v_cndmask_b32_e64 v33, 0, 32, vcc
	v_ldexp_f32 v33, v67, v33
	v_log_f32_e32 v33, v33
	s_nop 0
	v_mul_f32_e32 v66, 0x3f317217, v33
	v_fma_f32 v66, v33, s95, -v66
	v_fmac_f32_e32 v66, 0x3377d1cf, v33
	v_fmac_f32_e32 v66, 0x3f317217, v33
	v_cmp_lt_f32_e64 s[0:1], |v33|, s88
	s_nop 1
	v_cndmask_b32_e64 v33, v33, v66, s[0:1]
	v_cndmask_b32_e32 v66, 0, v213, vcc
	v_sub_f32_e32 v33, v33, v66
	v_add_f32_e32 v66, v45, v33
	s_waitcnt vmcnt(25)
	v_lshlrev_b32_e32 v33, 16, v177
	v_mul_f32_e32 v33, 0xbfb8aa3b, v33
	v_exp_f32_e32 v33, v33
	s_nop 0
	v_add_f32_e32 v33, 1.0, v33
	v_rcp_f32_e32 v33, v33
	s_nop 0
	v_fma_f32 v108, v71, v33, v70
	v_cmp_gt_f32_e32 vcc, s71, v108
	s_nop 1
	v_cndmask_b32_e64 v33, 0, 32, vcc
	v_ldexp_f32 v33, v108, v33
	v_log_f32_e32 v33, v33
	s_nop 0
	v_mul_f32_e32 v107, 0x3f317217, v33
	v_fma_f32 v107, v33, s95, -v107
	v_fmac_f32_e32 v107, 0x3377d1cf, v33
	v_fmac_f32_e32 v107, 0x3f317217, v33
	v_cmp_lt_f32_e64 s[0:1], |v33|, s88
	s_nop 1
	v_cndmask_b32_e64 v33, v33, v107, s[0:1]
	v_cndmask_b32_e32 v107, 0, v213, vcc
	v_sub_f32_e32 v33, v33, v107
	v_add_f32_e32 v107, v66, v33
	s_waitcnt vmcnt(23)
	v_lshlrev_b32_e32 v33, 16, v178
	v_mul_f32_e32 v33, 0xbfb8aa3b, v33
	v_exp_f32_e32 v33, v33
	s_nop 0
	v_add_f32_e32 v33, 1.0, v33
	v_rcp_f32_e32 v33, v33
	s_nop 0
	v_fma_f32 v111, v71, v33, v70
	v_cmp_gt_f32_e32 vcc, s71, v111
	s_nop 1
	v_cndmask_b32_e64 v33, 0, 32, vcc
	v_ldexp_f32 v33, v111, v33
	v_log_f32_e32 v33, v33
	s_nop 0
	v_mul_f32_e32 v110, 0x3f317217, v33
	v_fma_f32 v110, v33, s95, -v110
	v_fmac_f32_e32 v110, 0x3377d1cf, v33
	v_fmac_f32_e32 v110, 0x3f317217, v33
	v_cmp_lt_f32_e64 s[0:1], |v33|, s88
	s_nop 1
	v_cndmask_b32_e64 v33, v33, v110, s[0:1]
	v_cndmask_b32_e32 v110, 0, v213, vcc
	v_sub_f32_e32 v33, v33, v110
	v_add_f32_e32 v110, v107, v33
	s_waitcnt vmcnt(21)
	v_lshlrev_b32_e32 v33, 16, v179
	v_mul_f32_e32 v33, 0xbfb8aa3b, v33
	v_exp_f32_e32 v33, v33
	s_nop 0
	v_add_f32_e32 v33, 1.0, v33
	v_rcp_f32_e32 v33, v33
	s_nop 0
	v_fma_f32 v114, v71, v33, v70
	v_cmp_gt_f32_e32 vcc, s71, v114
	s_nop 1
	v_cndmask_b32_e64 v33, 0, 32, vcc
	v_ldexp_f32 v33, v114, v33
	v_log_f32_e32 v33, v33
	s_nop 0
	v_mul_f32_e32 v113, 0x3f317217, v33
	v_fma_f32 v113, v33, s95, -v113
	v_fmac_f32_e32 v113, 0x3377d1cf, v33
	v_fmac_f32_e32 v113, 0x3f317217, v33
	v_cmp_lt_f32_e64 s[0:1], |v33|, s88
	s_nop 1
	v_cndmask_b32_e64 v33, v33, v113, s[0:1]
	v_cndmask_b32_e32 v113, 0, v213, vcc
	v_sub_f32_e32 v33, v33, v113
	v_add_f32_e32 v113, v110, v33
	s_waitcnt vmcnt(19)
; __device__ __forceinline__ float bf2f(unsigned short h) { return __uint_as_float(((unsigned)h) << 16); }
; __device__ __forceinline__ float sigmoidf_(float x) { return __builtin_amdgcn_rcpf(1.f + __expf(-x)); }
; template <int MODE> __device__ __forceinline__ void hgrn_unit(LAS unsigned char* lds, const Params& P, int unit) {
;     ...
; #pragma unroll
;         for (int i = 0; i < 16; ++i) {
;             const size_t ro = (size_t)(t0 + 16 * g + i) * 4096 + h * 128 + k;
;             const float x = bf2f(ZA[ro + 1024]);
;             const float f = lb + (1.f - lb) * sigmoidf_(x);
;             run += __logf(f); bb[i] = run; kk[i] = 1.f - f;
;             if (MODE == 1) qq[i] = bf2f(ZA[ro]);
;         }
;         SEG[g * 128 + k] = run;
;         __syncthreads();
;         const float s0 = SEG[k], s1 = SEG[128 + k], s2 = SEG[256 + k], s3 = SEG[384 + k];
;         const float pre = (g > 0 ? s0 : 0.f) + (g > 1 ? s1 : 0.f) + (g > 2 ? s2 : 0.f);
;         const float btot = (s0 + s1) + (s2 + s3), ref = s0 + s1;
;         if (g == 0) { const float e = __expf(btot); DL[k] = e; Dacc *= e; }
	v_lshlrev_b32_e32 v33, 16, v182
	v_mul_f32_e32 v33, 0xbfb8aa3b, v33
	v_exp_f32_e32 v33, v33
	s_nop 0
	v_add_f32_e32 v33, 1.0, v33
	v_rcp_f32_e32 v33, v33
	s_nop 0
	v_fma_f32 v117, v71, v33, v70
	v_cmp_gt_f32_e32 vcc, s71, v117
	s_nop 1
	v_cndmask_b32_e64 v33, 0, 32, vcc
	v_ldexp_f32 v33, v117, v33
	v_log_f32_e32 v33, v33
	s_nop 0
	v_mul_f32_e32 v116, 0x3f317217, v33
	v_fma_f32 v116, v33, s95, -v116
	v_fmac_f32_e32 v116, 0x3377d1cf, v33
	v_fmac_f32_e32 v116, 0x3f317217, v33
	v_cmp_lt_f32_e64 s[0:1], |v33|, s88
	s_nop 1
	v_cndmask_b32_e64 v33, v33, v116, s[0:1]
	v_cndmask_b32_e32 v116, 0, v213, vcc
	v_sub_f32_e32 v33, v33, v116
	v_add_f32_e32 v116, v113, v33
	s_waitcnt vmcnt(17)
	v_lshlrev_b32_e32 v33, 16, v183
	v_mul_f32_e32 v33, 0xbfb8aa3b, v33
	v_exp_f32_e32 v33, v33
	s_nop 0
	v_add_f32_e32 v33, 1.0, v33
	v_rcp_f32_e32 v33, v33
	s_nop 0
	v_fma_f32 v120, v71, v33, v70
	v_cmp_gt_f32_e32 vcc, s71, v120
	s_nop 1
	v_cndmask_b32_e64 v33, 0, 32, vcc
	v_ldexp_f32 v33, v120, v33
	v_log_f32_e32 v33, v33
	s_nop 0
	v_mul_f32_e32 v119, 0x3f317217, v33
	v_fma_f32 v119, v33, s95, -v119
	v_fmac_f32_e32 v119, 0x3377d1cf, v33
	v_fmac_f32_e32 v119, 0x3f317217, v33
	v_cmp_lt_f32_e64 s[0:1], |v33|, s88
	s_nop 1
	v_cndmask_b32_e64 v33, v33, v119, s[0:1]
	v_cndmask_b32_e32 v119, 0, v213, vcc
	v_sub_f32_e32 v33, v33, v119
	v_add_f32_e32 v119, v116, v33
	s_waitcnt vmcnt(15)
	v_lshlrev_b32_e32 v33, 16, v184
	v_mul_f32_e32 v33, 0xbfb8aa3b, v33
	v_exp_f32_e32 v33, v33
	s_nop 0
	v_add_f32_e32 v33, 1.0, v33
	v_rcp_f32_e32 v33, v33
	s_nop 0
	v_fma_f32 v123, v71, v33, v70
	v_cmp_gt_f32_e32 vcc, s71, v123
	s_nop 1
	v_cndmask_b32_e64 v33, 0, 32, vcc
	v_ldexp_f32 v33, v123, v33
	v_log_f32_e32 v33, v33
	s_nop 0
	v_mul_f32_e32 v122, 0x3f317217, v33
	v_fma_f32 v122, v33, s95, -v122
	v_fmac_f32_e32 v122, 0x3377d1cf, v33
	v_fmac_f32_e32 v122, 0x3f317217, v33
	v_cmp_lt_f32_e64 s[0:1], |v33|, s88
	s_nop 1
	v_cndmask_b32_e64 v33, v33, v122, s[0:1]
	v_cndmask_b32_e32 v122, 0, v213, vcc
	v_sub_f32_e32 v33, v33, v122
	v_add_f32_e32 v122, v119, v33
	s_waitcnt vmcnt(13)
	v_lshlrev_b32_e32 v33, 16, v185
	v_mul_f32_e32 v33, 0xbfb8aa3b, v33
	v_exp_f32_e32 v33, v33
	s_nop 0
	v_add_f32_e32 v33, 1.0, v33
	v_rcp_f32_e32 v33, v33
	s_nop 0
	v_fma_f32 v126, v71, v33, v70
	v_cmp_gt_f32_e32 vcc, s71, v126
	s_nop 1
	v_cndmask_b32_e64 v33, 0, 32, vcc
	v_ldexp_f32 v33, v126, v33
	v_log_f32_e32 v33, v33
	s_nop 0
	v_mul_f32_e32 v125, 0x3f317217, v33
	v_fma_f32 v125, v33, s95, -v125
	v_fmac_f32_e32 v125, 0x3377d1cf, v33
	v_fmac_f32_e32 v125, 0x3f317217, v33
	v_cmp_lt_f32_e64 s[0:1], |v33|, s88
	s_nop 1
	v_cndmask_b32_e64 v33, v33, v125, s[0:1]
	v_cndmask_b32_e32 v125, 0, v213, vcc
	v_sub_f32_e32 v33, v33, v125
	v_add_f32_e32 v125, v122, v33
	s_waitcnt vmcnt(11)
	v_lshlrev_b32_e32 v33, 16, v186
	v_mul_f32_e32 v33, 0xbfb8aa3b, v33
	v_exp_f32_e32 v33, v33
	s_nop 0
	v_add_f32_e32 v33, 1.0, v33
	v_rcp_f32_e32 v33, v33
	s_nop 0
	v_fma_f32 v129, v71, v33, v70
	v_cmp_gt_f32_e32 vcc, s71, v129
	s_nop 1
	v_cndmask_b32_e64 v33, 0, 32, vcc
	v_ldexp_f32 v33, v129, v33
	v_log_f32_e32 v33, v33
	s_nop 0
	v_mul_f32_e32 v128, 0x3f317217, v33
	v_fma_f32 v128, v33, s95, -v128
	v_fmac_f32_e32 v128, 0x3377d1cf, v33
	v_fmac_f32_e32 v128, 0x3f317217, v33
	v_cmp_lt_f32_e64 s[0:1], |v33|, s88
	s_nop 1
	v_cndmask_b32_e64 v33, v33, v128, s[0:1]
	v_cndmask_b32_e32 v128, 0, v213, vcc
	v_sub_f32_e32 v33, v33, v128
	v_add_f32_e32 v128, v125, v33
	s_waitcnt vmcnt(9)
	v_lshlrev_b32_e32 v33, 16, v187
	v_mul_f32_e32 v33, 0xbfb8aa3b, v33
	v_exp_f32_e32 v33, v33
	s_nop 0
	v_add_f32_e32 v33, 1.0, v33
	v_rcp_f32_e32 v33, v33
	s_nop 0
	v_fma_f32 v132, v71, v33, v70
	v_cmp_gt_f32_e32 vcc, s71, v132
	s_nop 1
	v_cndmask_b32_e64 v33, 0, 32, vcc
	v_ldexp_f32 v33, v132, v33
	v_log_f32_e32 v33, v33
	s_nop 0
	v_mul_f32_e32 v131, 0x3f317217, v33
	v_fma_f32 v131, v33, s95, -v131
	v_fmac_f32_e32 v131, 0x3377d1cf, v33
	v_fmac_f32_e32 v131, 0x3f317217, v33
	v_cmp_lt_f32_e64 s[0:1], |v33|, s88
	s_nop 1
	v_cndmask_b32_e64 v33, v33, v131, s[0:1]
	v_cndmask_b32_e32 v131, 0, v213, vcc
	v_sub_f32_e32 v33, v33, v131
	v_add_f32_e32 v131, v128, v33
	s_waitcnt vmcnt(7)
	v_lshlrev_b32_e32 v33, 16, v188
	v_mul_f32_e32 v33, 0xbfb8aa3b, v33
	v_exp_f32_e32 v33, v33
	s_nop 0
	v_add_f32_e32 v33, 1.0, v33
	v_rcp_f32_e32 v33, v33
	s_nop 0
	v_fma_f32 v137, v71, v33, v70
	v_cmp_gt_f32_e32 vcc, s71, v137
	s_nop 1
	v_cndmask_b32_e64 v33, 0, 32, vcc
	v_ldexp_f32 v33, v137, v33
	v_log_f32_e32 v33, v33
	s_nop 0
	v_mul_f32_e32 v134, 0x3f317217, v33
	v_fma_f32 v134, v33, s95, -v134
	v_fmac_f32_e32 v134, 0x3377d1cf, v33
	v_fmac_f32_e32 v134, 0x3f317217, v33
	v_cmp_lt_f32_e64 s[0:1], |v33|, s88
	s_nop 1
	v_cndmask_b32_e64 v33, v33, v134, s[0:1]
	v_cndmask_b32_e32 v134, 0, v213, vcc
	v_sub_f32_e32 v33, v33, v134
	v_add_f32_e32 v136, v131, v33
	s_waitcnt vmcnt(5)
	v_lshlrev_b32_e32 v34, 16, v189
	v_mul_f32_e32 v34, 0xbfb8aa3b, v34
	v_exp_f32_e32 v34, v34
	s_nop 0
	v_add_f32_e32 v34, 1.0, v34
	v_rcp_f32_e32 v34, v34
	s_nop 0
	v_fma_f32 v146, v71, v34, v70
	v_cmp_gt_f32_e32 vcc, s71, v146
	s_nop 1
	v_cndmask_b32_e64 v34, 0, 32, vcc
	v_ldexp_f32 v34, v146, v34
	v_log_f32_e32 v34, v34
	s_nop 0
	v_mul_f32_e32 v35, 0x3f317217, v34
	v_fma_f32 v35, v34, s95, -v35
	v_fmac_f32_e32 v35, 0x3377d1cf, v34
	v_fmac_f32_e32 v35, 0x3f317217, v34
	v_cmp_lt_f32_e64 s[0:1], |v34|, s88
	s_nop 1
	v_cndmask_b32_e64 v34, v34, v35, s[0:1]
	v_cndmask_b32_e32 v35, 0, v213, vcc
	v_sub_f32_e32 v34, v34, v35
	v_add_f32_e32 v145, v136, v34
	ds_write_b32 v72, v145
	s_waitcnt lgkmcnt(0)
	s_barrier
	ds_read2st64_b32 v[34:35], v73 offset1:2
	ds_read2st64_b32 v[32:33], v73 offset0:4 offset1:6
	s_waitcnt lgkmcnt(1)
	v_add_f32_e32 v155, v34, v35
	s_waitcnt lgkmcnt(0)
	v_add_f32_e32 v33, v32, v33
	v_add_f32_e32 v33, v155, v33
	s_and_saveexec_b64 s[0:1], s[28:29]
	s_cbranch_execz .LBB0_227
	v_mul_f32_e32 v134, 0x3fb8aa3b, v33
	v_exp_f32_e32 v134, v134
	ds_write_b32 v80, v134

; #define PG8_STAGE(bufoff, gbase, voff) do { _Pragma("unroll") for (int _i = 0; _i < 2; ++_i) \
;         __builtin_amdgcn_global_load_lds((const unsigned*)((const char*)(gbase) + (voff)[_i]), (PG8_LAS unsigned*)(lds + (bufoff) + ldsw + _i * 8192), 16, 0, 0); } while (0)
; #define PG8_WAIT_V(n) asm volatile("s_waitcnt vmcnt(" #n ")" ::: "memory")
; #define PG8_WAIT_L(n) asm volatile("s_waitcnt lgkmcnt(" #n ")" ::: "memory")
; #define PG8_BAR __builtin_amdgcn_s_barrier()
; template <class Epi, class Sched, bool ALIGN_EPI = false, bool SP2 = false>
; __device__ __forceinline__ void gemm_phase(PG8_LAS unsigned char* lds, const Gemm g, const Sched& S, const Epi& E) {
;     ...
;         for (int t = 0; t < nt; t += 2) {
;             const bool last = (t == nt - 2);
;             const char* a1 = cA + (size_t)(t + 1) * kstep;
;             const char* a2 = last ? nA : cA + (size_t)(t + 2) * kstep; const char* b2 = last ? nB : cB + (size_t)(t + 2) * kstep;
;             const char* a3 = a2 + kstep; const char* b3 = b2 + kstep;
;             if (last && has_next) S.a_ready(nxt);
;             if constexpr (SP2) {
;             PG8_LDB(B0, 0, 0); PG8_LDB(B1, 0, 1); PG8_SCHED; PG8_LDA(At, 0, 0); PG8_STAGE(PG8_SA(1, 1), a1 + hstepA, voffA);
;             PG8_WAIT_V(8); PG8_WAIT_L(0); PG8_BAR; PG8_MMA(0, 0, At, B0); PG8_MMA(0, 1, At, B1); PG8_BAR; PG8_SCHED;
;             PG8_LDA(At, 0, 1); PG8_STAGE(PG8_SB(0, 0), b2, voffB); PG8_STAGE(PG8_SB(0, 1), b2 + hstepB, voffB); PG8_STAGE(PG8_SA(0, 0), a2, voffA);
;             PG8_WAIT_V(8); PG8_WAIT_L(0); PG8_BAR; PG8_MMA(1, 0, At, B0); PG8_MMA(1, 1, At, B1); PG8_BAR; PG8_SCHED;
;             PG8_LDB(B0, 1, 0); PG8_LDB(B1, 1, 1); PG8_SCHED; PG8_LDA(At, 1, 0); PG8_STAGE(PG8_SA(0, 1), a2 + hstepA, voffA);
;             PG8_WAIT_V(8); PG8_WAIT_L(0); PG8_BAR; PG8_MMA(0, 0, At, B0); PG8_MMA(0, 1, At, B1); PG8_BAR; PG8_SCHED;
;             PG8_LDA(At, 1, 1); PG8_STAGE(PG8_SB(1, 0), b3, voffB); PG8_STAGE(PG8_SB(1, 1), b3 + hstepB, voffB); PG8_STAGE(PG8_SA(1, 0), a3, voffA);
;             PG8_WAIT_V(8); PG8_WAIT_L(0); PG8_BAR; PG8_MMA(1, 0, At, B0); PG8_MMA(1, 1, At, B1); PG8_BAR; PG8_SCHED;
;     __device__ __forceinline__ void operator()(const f32x4 (&acc)[2][2][4][2], const pg8::Unit& u, int wr, int wc, int fr, int fq) const {
;     ...
;                     const f32x4 bs0 = *(const f32x4*)(base + o), bs1 = *(const f32x4*)(base + o + 4);
.LBB0_468:
	s_add_i32 s76, s28, 2
	s_add_u32 s48, s26, 0x80
	s_addc_u32 s29, s27, 0
	s_add_i32 s49, 0, 0x10000
	s_cmp_eq_u32 s45, s28
	s_cselect_b32 s29, s1, s29
	s_cselect_b32 s28, s0, s48
	s_cselect_b32 s79, s25, s73
	s_cselect_b32 s78, s24, s72
	s_add_i32 s48, s28, 8
	s_cmp_eq_u32 s48, s45
	s_cbranch_scc0 .Ltouch0_skip
	s_lshl_b32 s48, s67, 21
	s_lshl_b32 vcc_lo, s66, 10
	s_add_i32 s48, s48, vcc_lo
	v_lshrrev_b32_e32 v234, 3, v202
	v_and_b32_e32 v235, 7, v234
	v_lshrrev_b32_e32 v234, 3, v234
	v_lshl_add_u32 v234, v234, 5, v235
	v_and_b32_e32 v235, 7, v202
	v_lshlrev_b32_e32 v235, 7, v235
	v_lshl_add_u32 v234, v234, 13, v235
	v_add_u32_e32 v234, s48, v234
	global_load_dword v236, v234, s[74:75]
	v_add_u32_e32 v235, 0x10000, v234
	global_load_dword v237, v235, s[74:75]
	v_add_u32_e32 v235, 0x20000, v234
	global_load_dword v238, v235, s[74:75]
	v_add_u32_e32 v235, 0x30000, v234
	global_load_dword v239, v235, s[74:75]
.Ltouch0_skip:
	s_add_i32 s48, 0, 0x14000
	v_add_u32_e32 v154, s49, v143
	v_add_u32_e32 v170, s48, v143
	ds_read_b128 v[138:141], v154
	ds_read_b128 v[146:149], v154 offset:1024
	ds_read_b128 v[150:153], v154 offset:2048
	ds_read_b128 v[154:157], v154 offset:3072
	ds_read_b128 v[158:161], v170
	ds_read_b128 v[162:165], v170 offset:1024
	ds_read_b128 v[166:169], v170 offset:2048
	ds_read_b128 v[170:173], v170 offset:3072
	v_lshl_add_u64 v[178:179], s[26:27], 0, v[134:135]
	s_add_i32 m0, s34, 0xc000
	ds_read_b128 v[174:177], v145
	ds_read_b128 v[182:185], v145 offset:1024
	ds_read_b128 v[186:189], v145 offset:2048
	ds_read_b128 v[190:193], v145 offset:3072
	ds_read_b128 v[194:197], v145 offset:4096
	ds_read_b128 v[198:201], v145 offset:5120
	ds_read_b128 v[214:217], v145 offset:6144
	ds_read_b128 v[218:221], v145 offset:7168
	global_load_lds_dwordx4 v[178:179], off
	v_lshl_add_u64 v[178:179], s[26:27], 0, v[136:137]
	s_add_i32 m0, s34, 0xe000
	s_nop 0
	global_load_lds_dwordx4 v[178:179], off
	s_waitcnt vmcnt(8)
	s_waitcnt lgkmcnt(0)
	s_barrier
	s_setprio 1
	s_waitcnt lgkmcnt(0)
	v_mfma_f32_16x16x32_bf16 v[124:127], v[138:141], v[174:177], v[124:127]
	v_mfma_f32_16x16x32_bf16 v[120:123], v[150:153], v[174:177], v[120:123]
	v_mfma_f32_16x16x32_bf16 v[108:111], v[138:141], v[186:189], v[108:111]
	v_mfma_f32_16x16x32_bf16 v[104:107], v[150:153], v[186:189], v[104:107]
	v_mfma_f32_16x16x32_bf16 v[92:95], v[138:141], v[194:197], v[92:95]
	v_mfma_f32_16x16x32_bf16 v[88:91], v[150:153], v[194:197], v[88:91]
	v_mfma_f32_16x16x32_bf16 v[76:79], v[138:141], v[214:217], v[76:79]
	v_mfma_f32_16x16x32_bf16 v[72:75], v[150:153], v[214:217], v[72:75]
	v_mfma_f32_16x16x32_bf16 v[124:127], v[146:149], v[182:185], v[124:127]
	v_mfma_f32_16x16x32_bf16 v[120:123], v[154:157], v[182:185], v[120:123]
	v_mfma_f32_16x16x32_bf16 v[108:111], v[146:149], v[190:193], v[108:111]
	v_mfma_f32_16x16x32_bf16 v[104:107], v[154:157], v[190:193], v[104:107]
	v_mfma_f32_16x16x32_bf16 v[92:95], v[146:149], v[198:201], v[92:95]
	v_mfma_f32_16x16x32_bf16 v[88:91], v[154:157], v[198:201], v[88:91]
	v_mfma_f32_16x16x32_bf16 v[76:79], v[146:149], v[218:221], v[76:79]
	v_mfma_f32_16x16x32_bf16 v[72:75], v[154:157], v[218:221], v[72:75]
	s_setprio 0
	s_setprio 1
	v_mfma_f32_16x16x32_bf16 v[116:119], v[158:161], v[174:177], v[116:119]
	v_mfma_f32_16x16x32_bf16 v[112:115], v[166:169], v[174:177], v[112:115]
	v_mfma_f32_16x16x32_bf16 v[100:103], v[158:161], v[186:189], v[100:103]
	v_mfma_f32_16x16x32_bf16 v[96:99], v[166:169], v[186:189], v[96:99]
	v_mfma_f32_16x16x32_bf16 v[84:87], v[158:161], v[194:197], v[84:87]
	v_mfma_f32_16x16x32_bf16 v[80:83], v[166:169], v[194:197], v[80:83]
	v_mfma_f32_16x16x32_bf16 v[68:71], v[158:161], v[214:217], v[68:71]
	v_mfma_f32_16x16x32_bf16 v[64:67], v[166:169], v[214:217], v[64:67]
	v_mfma_f32_16x16x32_bf16 v[116:119], v[162:165], v[182:185], v[116:119]
	v_mfma_f32_16x16x32_bf16 v[112:115], v[170:173], v[182:185], v[112:115]
	v_mfma_f32_16x16x32_bf16 v[100:103], v[162:165], v[190:193], v[100:103]
	v_mfma_f32_16x16x32_bf16 v[96:99], v[170:173], v[190:193], v[96:99]
	v_mfma_f32_16x16x32_bf16 v[84:87], v[162:165], v[198:201], v[84:87]
	v_mfma_f32_16x16x32_bf16 v[80:83], v[170:173], v[198:201], v[80:83]
	v_mfma_f32_16x16x32_bf16 v[68:71], v[162:165], v[218:221], v[68:71]
	v_mfma_f32_16x16x32_bf16 v[64:67], v[170:173], v[218:221], v[64:67]
	s_setprio 0
	s_barrier
	s_add_i32 s49, s49, s17
	v_lshl_add_u64 v[178:179], s[78:79], 0, v[180:181]
	s_mov_b32 m0, s49
	ds_read_b128 v[174:177], v145 offset:16384
	ds_read_b128 v[182:185], v145 offset:17408
	ds_read_b128 v[186:189], v145 offset:18432
	ds_read_b128 v[190:193], v145 offset:19456
	ds_read_b128 v[194:197], v145 offset:20480
	ds_read_b128 v[198:201], v145 offset:21504
	ds_read_b128 v[214:217], v145 offset:22528
	ds_read_b128 v[218:221], v145 offset:23552
	global_load_lds_dwordx4 v[178:179], off
	s_add_i32 m0, s49, 0x2000
	v_lshl_add_u64 v[222:223], s[78:79], 0, v[132:133]
	s_add_u32 s78, s78, s2
	s_addc_u32 s79, s79, 0
	s_add_i32 s48, s48, s17
	global_load_lds_dwordx4 v[222:223], off
	v_lshl_add_u64 v[224:225], s[78:79], 0, v[180:181]
	s_mov_b32 m0, s48
	v_lshl_add_u64 v[226:227], s[78:79], 0, v[132:133]
	global_load_lds_dwordx4 v[224:225], off
	s_add_i32 m0, s48, 0x2000
	v_lshl_add_u64 v[228:229], s[28:29], 0, v[128:129]
	global_load_lds_dwordx4 v[226:227], off
	s_mov_b32 m0, s34
	v_lshl_add_u64 v[230:231], s[28:29], 0, v[130:131]
	global_load_lds_dwordx4 v[228:229], off
	s_mov_b32 m0, s35
	s_nop 0
	global_load_lds_dwordx4 v[230:231], off
	s_waitcnt vmcnt(8)
	s_waitcnt lgkmcnt(0)
	s_barrier
; #define PG8_STAGE(bufoff, gbase, voff) do { _Pragma("unroll") for (int _i = 0; _i < 2; ++_i) \
;         __builtin_amdgcn_global_load_lds((const unsigned*)((const char*)(gbase) + (voff)[_i]), (PG8_LAS unsigned*)(lds + (bufoff) + ldsw + _i * 8192), 16, 0, 0); } while (0)
; #define PG8_LDA(dst, b, h) do { _Pragma("unroll") for (int m = 0; m < 4; ++m) _Pragma("unroll") for (int k = 0; k < 2; ++k) dst[m][k] = *(const PG8_LAS bf16x8*)(lds + PG8_SA(b, h) + aoff + m * 2048 + k * 1024); } while (0)
; #define PG8_LDB(dst, b, h) do { _Pragma("unroll") for (int n = 0; n < 2; ++n) _Pragma("unroll") for (int k = 0; k < 2; ++k) dst[n][k] = *(const PG8_LAS bf16x8*)(lds + PG8_SB(b, h) + boff + n * 2048 + k * 1024); } while (0)
; #define PG8_MMA(ai, bj, At, Bt) do { __builtin_amdgcn_s_setprio(1); _Pragma("unroll") for (int m = 0; m < 4; ++m) _Pragma("unroll") for (int n = 0; n < 2; ++n) _Pragma("unroll") for (int k = 0; k < 2; ++k) \
;         acc[ai][bj][m][n] = __builtin_amdgcn_mfma_f32_16x16x32_bf16(Bt[n][k], At[m][k], acc[ai][bj][m][n], 0, 0, 0); __builtin_amdgcn_s_setprio(0); } while (0)
; #define PG8_WAIT_V(n) asm volatile("s_waitcnt vmcnt(" #n ")" ::: "memory")
; #define PG8_WAIT_L(n) asm volatile("s_waitcnt lgkmcnt(" #n ")" ::: "memory")
; #define PG8_BAR __builtin_amdgcn_s_barrier()
; #define PG8_SCHED __builtin_amdgcn_sched_barrier(0)
; template <class Epi, class Sched, bool ALIGN_EPI = false, bool SP2 = false>
; __device__ __forceinline__ void gemm_phase(PG8_LAS unsigned char* lds, const Gemm g, const Sched& S, const Epi& E) {
;     ...
;             PG8_WAIT_V(8); PG8_WAIT_L(0); PG8_BAR; PG8_MMA(1, 0, At, B0); PG8_MMA(1, 1, At, B1); PG8_BAR; PG8_SCHED;
;             PG8_LDB(B0, 1, 0); PG8_LDB(B1, 1, 1); PG8_SCHED; PG8_LDA(At, 1, 0); PG8_STAGE(PG8_SA(0, 1), a2 + hstepA, voffA);
;             PG8_WAIT_V(8); PG8_WAIT_L(0); PG8_BAR; PG8_MMA(0, 0, At, B0); PG8_MMA(0, 1, At, B1); PG8_BAR; PG8_SCHED;
	s_setprio 1
	s_waitcnt lgkmcnt(0)
	v_mfma_f32_16x16x32_bf16 v[60:63], v[138:141], v[174:177], v[60:63]
	v_mfma_f32_16x16x32_bf16 v[56:59], v[150:153], v[174:177], v[56:59]
	v_mfma_f32_16x16x32_bf16 v[44:47], v[138:141], v[186:189], v[44:47]
	v_mfma_f32_16x16x32_bf16 v[40:43], v[150:153], v[186:189], v[40:43]
	v_mfma_f32_16x16x32_bf16 v[28:31], v[138:141], v[194:197], v[28:31]
	v_mfma_f32_16x16x32_bf16 v[24:27], v[150:153], v[194:197], v[24:27]
	v_mfma_f32_16x16x32_bf16 v[12:15], v[138:141], v[214:217], v[12:15]
	v_mfma_f32_16x16x32_bf16 v[8:11], v[150:153], v[214:217], v[8:11]
	v_mfma_f32_16x16x32_bf16 v[60:63], v[146:149], v[182:185], v[60:63]
	v_mfma_f32_16x16x32_bf16 v[56:59], v[154:157], v[182:185], v[56:59]
	v_mfma_f32_16x16x32_bf16 v[44:47], v[146:149], v[190:193], v[44:47]
	v_mfma_f32_16x16x32_bf16 v[40:43], v[154:157], v[190:193], v[40:43]
	v_mfma_f32_16x16x32_bf16 v[28:31], v[146:149], v[198:201], v[28:31]
	v_mfma_f32_16x16x32_bf16 v[24:27], v[154:157], v[198:201], v[24:27]
	v_mfma_f32_16x16x32_bf16 v[12:15], v[146:149], v[218:221], v[12:15]
	v_mfma_f32_16x16x32_bf16 v[8:11], v[154:157], v[218:221], v[8:11]
	s_setprio 0
	s_setprio 1
	v_mfma_f32_16x16x32_bf16 v[52:55], v[158:161], v[174:177], v[52:55]
	v_mfma_f32_16x16x32_bf16 v[48:51], v[166:169], v[174:177], v[48:51]
	v_mfma_f32_16x16x32_bf16 v[36:39], v[158:161], v[186:189], v[36:39]
	v_mfma_f32_16x16x32_bf16 v[32:35], v[166:169], v[186:189], v[32:35]
	v_mfma_f32_16x16x32_bf16 v[20:23], v[158:161], v[194:197], v[20:23]
	v_mfma_f32_16x16x32_bf16 v[16:19], v[166:169], v[194:197], v[16:19]
	v_mfma_f32_16x16x32_bf16 v[4:7], v[158:161], v[214:217], v[4:7]
	v_mfma_f32_16x16x32_bf16 v[0:3], v[166:169], v[214:217], v[0:3]
	v_mfma_f32_16x16x32_bf16 v[52:55], v[162:165], v[182:185], v[52:55]
	v_mfma_f32_16x16x32_bf16 v[48:51], v[170:173], v[182:185], v[48:51]
	v_mfma_f32_16x16x32_bf16 v[36:39], v[162:165], v[190:193], v[36:39]
	v_mfma_f32_16x16x32_bf16 v[32:35], v[170:173], v[190:193], v[32:35]
	v_mfma_f32_16x16x32_bf16 v[20:23], v[162:165], v[198:201], v[20:23]
	v_mfma_f32_16x16x32_bf16 v[16:19], v[170:173], v[198:201], v[16:19]
	v_mfma_f32_16x16x32_bf16 v[4:7], v[162:165], v[218:221], v[4:7]
	v_mfma_f32_16x16x32_bf16 v[0:3], v[170:173], v[218:221], v[0:3]
	s_setprio 0
	s_barrier
	s_add_i32 s48, 0, 0x18000
	s_add_i32 s49, 0, 0x1c000
	v_add_u32_e32 v154, s48, v143
	v_add_u32_e32 v170, s49, v143
	ds_read_b128 v[138:141], v154
	ds_read_b128 v[146:149], v154 offset:1024
	ds_read_b128 v[150:153], v154 offset:2048
	ds_read_b128 v[154:157], v154 offset:3072
	ds_read_b128 v[158:161], v170
	ds_read_b128 v[162:165], v170 offset:1024
	ds_read_b128 v[166:169], v170 offset:2048
	ds_read_b128 v[170:173], v170 offset:3072
	s_add_u32 s28, s28, s22
	s_addc_u32 s29, s29, 0
	s_mov_b32 m0, s36
	v_lshl_add_u64 v[232:233], s[28:29], 0, v[128:129]
	ds_read_b128 v[174:177], v145 offset:32768
	ds_read_b128 v[182:185], v145 offset:33792
	ds_read_b128 v[186:189], v145 offset:34816
	ds_read_b128 v[190:193], v145 offset:35840
	ds_read_b128 v[194:197], v145 offset:36864
	ds_read_b128 v[198:201], v145 offset:37888
	ds_read_b128 v[214:217], v145 offset:38912
	ds_read_b128 v[218:221], v145 offset:39936
	global_load_lds_dwordx4 v[232:233], off
	v_lshl_add_u64 v[232:233], s[28:29], 0, v[130:131]
	s_mov_b32 m0, s37
	s_nop 0
	global_load_lds_dwordx4 v[232:233], off
	s_waitcnt vmcnt(8)
	s_waitcnt lgkmcnt(0)
	s_barrier
	s_setprio 1
	s_waitcnt lgkmcnt(0)
	v_mfma_f32_16x16x32_bf16 v[124:127], v[138:141], v[174:177], v[124:127]
	v_mfma_f32_16x16x32_bf16 v[120:123], v[150:153], v[174:177], v[120:123]
	v_mfma_f32_16x16x32_bf16 v[108:111], v[138:141], v[186:189], v[108:111]
	v_mfma_f32_16x16x32_bf16 v[104:107], v[150:153], v[186:189], v[104:107]
	v_mfma_f32_16x16x32_bf16 v[92:95], v[138:141], v[194:197], v[92:95]
	v_mfma_f32_16x16x32_bf16 v[88:91], v[150:153], v[194:197], v[88:91]
	v_mfma_f32_16x16x32_bf16 v[76:79], v[138:141], v[214:217], v[76:79]
	v_mfma_f32_16x16x32_bf16 v[72:75], v[150:153], v[214:217], v[72:75]
	v_mfma_f32_16x16x32_bf16 v[124:127], v[146:149], v[182:185], v[124:127]
	v_mfma_f32_16x16x32_bf16 v[120:123], v[154:157], v[182:185], v[120:123]
	v_mfma_f32_16x16x32_bf16 v[108:111], v[146:149], v[190:193], v[108:111]
	v_mfma_f32_16x16x32_bf16 v[104:107], v[154:157], v[190:193], v[104:107]
	v_mfma_f32_16x16x32_bf16 v[92:95], v[146:149], v[198:201], v[92:95]
	v_mfma_f32_16x16x32_bf16 v[88:91], v[154:157], v[198:201], v[88:91]
	v_mfma_f32_16x16x32_bf16 v[76:79], v[146:149], v[218:221], v[76:79]
	v_mfma_f32_16x16x32_bf16 v[72:75], v[154:157], v[218:221], v[72:75]
	s_setprio 0
	s_setprio 1
	v_mfma_f32_16x16x32_bf16 v[116:119], v[158:161], v[174:177], v[116:119]
	v_mfma_f32_16x16x32_bf16 v[112:115], v[166:169], v[174:177], v[112:115]
	v_mfma_f32_16x16x32_bf16 v[100:103], v[158:161], v[186:189], v[100:103]
	v_mfma_f32_16x16x32_bf16 v[96:99], v[166:169], v[186:189], v[96:99]
	v_mfma_f32_16x16x32_bf16 v[84:87], v[158:161], v[194:197], v[84:87]
	v_mfma_f32_16x16x32_bf16 v[80:83], v[166:169], v[194:197], v[80:83]
	v_mfma_f32_16x16x32_bf16 v[68:71], v[158:161], v[214:217], v[68:71]
	v_mfma_f32_16x16x32_bf16 v[64:67], v[166:169], v[214:217], v[64:67]
	v_mfma_f32_16x16x32_bf16 v[116:119], v[162:165], v[182:185], v[116:119]
	v_mfma_f32_16x16x32_bf16 v[112:115], v[170:173], v[182:185], v[112:115]
	v_mfma_f32_16x16x32_bf16 v[100:103], v[162:165], v[190:193], v[100:103]
	v_mfma_f32_16x16x32_bf16 v[96:99], v[170:173], v[190:193], v[96:99]
	v_mfma_f32_16x16x32_bf16 v[84:87], v[162:165], v[198:201], v[84:87]
	v_mfma_f32_16x16x32_bf16 v[80:83], v[170:173], v[198:201], v[80:83]
	v_mfma_f32_16x16x32_bf16 v[68:71], v[162:165], v[218:221], v[68:71]
	v_mfma_f32_16x16x32_bf16 v[64:67], v[170:173], v[218:221], v[64:67]
	s_setprio 0
	s_barrier
; #define PG8_STAGE(bufoff, gbase, voff) do { _Pragma("unroll") for (int _i = 0; _i < 2; ++_i) \
;         __builtin_amdgcn_global_load_lds((const unsigned*)((const char*)(gbase) + (voff)[_i]), (PG8_LAS unsigned*)(lds + (bufoff) + ldsw + _i * 8192), 16, 0, 0); } while (0)
; #define PG8_LDA(dst, b, h) do { _Pragma("unroll") for (int m = 0; m < 4; ++m) _Pragma("unroll") for (int k = 0; k < 2; ++k) dst[m][k] = *(const PG8_LAS bf16x8*)(lds + PG8_SA(b, h) + aoff + m * 2048 + k * 1024); } while (0)
; #define PG8_MMA(ai, bj, At, Bt) do { __builtin_amdgcn_s_setprio(1); _Pragma("unroll") for (int m = 0; m < 4; ++m) _Pragma("unroll") for (int n = 0; n < 2; ++n) _Pragma("unroll") for (int k = 0; k < 2; ++k) \
;         acc[ai][bj][m][n] = __builtin_amdgcn_mfma_f32_16x16x32_bf16(Bt[n][k], At[m][k], acc[ai][bj][m][n], 0, 0, 0); __builtin_amdgcn_s_setprio(0); } while (0)
; #define PG8_WAIT_V(n) asm volatile("s_waitcnt vmcnt(" #n ")" ::: "memory")
; #define PG8_WAIT_L(n) asm volatile("s_waitcnt lgkmcnt(" #n ")" ::: "memory")
; #define PG8_BAR __builtin_amdgcn_s_barrier()
; #define PG8_SCHED __builtin_amdgcn_sched_barrier(0)
; template <class Epi, class Sched, bool ALIGN_EPI = false, bool SP2 = false>
; __device__ __forceinline__ void gemm_phase(PG8_LAS unsigned char* lds, const Gemm g, const Sched& S, const Epi& E) {
;     ...
;         for (int t = 0; t < nt; t += 2) {
;     ...
;             PG8_LDA(At, 1, 1); PG8_STAGE(PG8_SB(1, 0), b3, voffB); PG8_STAGE(PG8_SB(1, 1), b3 + hstepB, voffB); PG8_STAGE(PG8_SA(1, 0), a3, voffA);
;             PG8_WAIT_V(8); PG8_WAIT_L(0); PG8_BAR; PG8_MMA(1, 0, At, B0); PG8_MMA(1, 1, At, B1); PG8_BAR; PG8_SCHED;
	s_add_i32 s28, s48, s17
	v_lshl_add_u64 v[178:179], v[178:179], 0, s[8:9]
	s_mov_b32 m0, s28
	ds_read_b128 v[174:177], v145 offset:49152
	ds_read_b128 v[182:185], v145 offset:50176
	ds_read_b128 v[186:189], v145 offset:51200
	ds_read_b128 v[190:193], v145 offset:52224
	ds_read_b128 v[194:197], v145 offset:53248
	ds_read_b128 v[198:201], v145 offset:54272
	ds_read_b128 v[214:217], v145 offset:55296
	ds_read_b128 v[218:221], v145 offset:56320
	global_load_lds_dwordx4 v[178:179], off
	v_lshl_add_u64 v[178:179], v[222:223], 0, s[8:9]
	s_add_i32 m0, s28, 0x2000
	s_add_i32 s28, s49, s17
	global_load_lds_dwordx4 v[178:179], off
	v_lshl_add_u64 v[178:179], v[224:225], 0, s[8:9]
	s_mov_b32 m0, s28
	s_nop 0
	global_load_lds_dwordx4 v[178:179], off
	v_lshl_add_u64 v[178:179], v[226:227], 0, s[8:9]
	s_add_i32 m0, s28, 0x2000
	s_nop 0
	global_load_lds_dwordx4 v[178:179], off
	v_lshl_add_u64 v[178:179], v[228:229], 0, s[8:9]
	s_mov_b32 m0, s42
	s_nop 0
	global_load_lds_dwordx4 v[178:179], off
	v_lshl_add_u64 v[178:179], v[230:231], 0, s[8:9]
	s_mov_b32 m0, s43
	s_nop 0
	global_load_lds_dwordx4 v[178:179], off
	s_waitcnt vmcnt(8)
	s_waitcnt lgkmcnt(0)
	s_barrier
	s_setprio 1
	s_waitcnt lgkmcnt(0)
	v_mfma_f32_16x16x32_bf16 v[60:63], v[138:141], v[174:177], v[60:63]
	v_mfma_f32_16x16x32_bf16 v[56:59], v[150:153], v[174:177], v[56:59]
	v_mfma_f32_16x16x32_bf16 v[44:47], v[138:141], v[186:189], v[44:47]
	v_mfma_f32_16x16x32_bf16 v[40:43], v[150:153], v[186:189], v[40:43]
	v_mfma_f32_16x16x32_bf16 v[28:31], v[138:141], v[194:197], v[28:31]
	v_mfma_f32_16x16x32_bf16 v[24:27], v[150:153], v[194:197], v[24:27]
	v_mfma_f32_16x16x32_bf16 v[12:15], v[138:141], v[214:217], v[12:15]
	v_mfma_f32_16x16x32_bf16 v[8:11], v[150:153], v[214:217], v[8:11]
	v_mfma_f32_16x16x32_bf16 v[60:63], v[146:149], v[182:185], v[60:63]
	v_mfma_f32_16x16x32_bf16 v[56:59], v[154:157], v[182:185], v[56:59]
	v_mfma_f32_16x16x32_bf16 v[44:47], v[146:149], v[190:193], v[44:47]
	v_mfma_f32_16x16x32_bf16 v[40:43], v[154:157], v[190:193], v[40:43]
	v_mfma_f32_16x16x32_bf16 v[28:31], v[146:149], v[198:201], v[28:31]
	v_mfma_f32_16x16x32_bf16 v[24:27], v[154:157], v[198:201], v[24:27]
	v_mfma_f32_16x16x32_bf16 v[12:15], v[146:149], v[218:221], v[12:15]
	v_mfma_f32_16x16x32_bf16 v[8:11], v[154:157], v[218:221], v[8:11]
	s_setprio 0
	s_setprio 1
	v_mfma_f32_16x16x32_bf16 v[52:55], v[158:161], v[174:177], v[52:55]
	v_mfma_f32_16x16x32_bf16 v[48:51], v[166:169], v[174:177], v[48:51]
	v_mfma_f32_16x16x32_bf16 v[36:39], v[158:161], v[186:189], v[36:39]
	v_mfma_f32_16x16x32_bf16 v[32:35], v[166:169], v[186:189], v[32:35]
	v_mfma_f32_16x16x32_bf16 v[20:23], v[158:161], v[194:197], v[20:23]
	v_mfma_f32_16x16x32_bf16 v[16:19], v[166:169], v[194:197], v[16:19]
	v_mfma_f32_16x16x32_bf16 v[4:7], v[158:161], v[214:217], v[4:7]
	v_mfma_f32_16x16x32_bf16 v[0:3], v[166:169], v[214:217], v[0:3]
	v_mfma_f32_16x16x32_bf16 v[52:55], v[162:165], v[182:185], v[52:55]
	v_mfma_f32_16x16x32_bf16 v[48:51], v[170:173], v[182:185], v[48:51]
	v_mfma_f32_16x16x32_bf16 v[36:39], v[162:165], v[190:193], v[36:39]
	v_mfma_f32_16x16x32_bf16 v[32:35], v[170:173], v[190:193], v[32:35]
	v_mfma_f32_16x16x32_bf16 v[20:23], v[162:165], v[198:201], v[20:23]
	v_mfma_f32_16x16x32_bf16 v[16:19], v[170:173], v[198:201], v[16:19]
	v_mfma_f32_16x16x32_bf16 v[4:7], v[162:165], v[218:221], v[4:7]
	v_mfma_f32_16x16x32_bf16 v[0:3], v[170:173], v[218:221], v[0:3]
	s_setprio 0
	s_barrier
	s_add_u32 s26, s26, 0x100
	s_addc_u32 s27, s27, 0
	s_add_u32 s72, s72, 0x100
	s_addc_u32 s73, s73, 0
	s_cmp_ge_u32 s76, s44
	s_mov_b32 s28, s76
	s_cbranch_scc0 .LBB0_468
	s_movk_i32 s78, 0x1000
	s_movk_i32 s79, 0x5100
	s_and_b64 vcc, exec, s[14:15]
	s_cbranch_vccz .LBB0_471

; __device__ __forceinline__ u32x2 pack4(f32x4 v) { u32x2 r; r.x = cvt_pk_bf16(v[0], v[1]); r.y = cvt_pk_bf16(v[2], v[3]); return r; }
; __device__ __forceinline__ void phase_prologue(const Params& P, LAS unsigned char* lds) {
;     ...
;     { const f32x4* s = (const f32x4*)P.in[1]; u32x2* d = (u32x2*)(ws + WS_PB); const size_t n4 = (size_t)2 * T_TOK * PLE_DIM / 4;
;       for (size_t i = GTID; i < n4; i += GTHREADS) d[i] = pack4(s[i]); }
.LBB0_730:
	s_or_b64 exec, exec, s[4:5]
	s_mov_b64 s[0:1], 0x400000
	v_cmp_gt_u64_e32 vcc, s[0:1], v[8:9]
	s_and_saveexec_b64 s[0:1], vcc
	v_readlane_b32 s6, v253, 45
	v_readlane_b32 s10, v253, 53
	v_readlane_b32 s7, v253, 46
	v_readlane_b32 s11, v253, 54
	s_cbranch_execz .LBB0_733
	v_readlane_b32 s2, v253, 42
	v_readlane_b32 s3, v253, 43
	s_mov_b64 s[4:5], 0
	s_nop 0
	v_lshl_add_u64 v[0:1], v[10:11], 4, s[2:3]
	v_readlane_b32 s2, v253, 47
	v_readlane_b32 s3, v253, 48
	s_nop 1
	v_lshl_add_u64 v[2:3], v[10:11], 3, s[2:3]
	s_cmp_eq_u32 s68, 0x20000
	s_cbranch_scc0 .LBB0_732
.Lpconv4:
	global_load_dwordx4 v[4:7], v[0:1], off
	v_lshl_add_u64 v[0:1], v[0:1], 0, s[6:7]
	global_load_dwordx4 v[12:15], v[0:1], off
	v_lshl_add_u64 v[0:1], v[0:1], 0, s[6:7]
	global_load_dwordx4 v[16:19], v[0:1], off
	v_lshl_add_u64 v[0:1], v[0:1], 0, s[6:7]
	global_load_dwordx4 v[20:23], v[0:1], off
	v_lshl_add_u64 v[0:1], v[0:1], 0, s[6:7]
	v_lshl_add_u64 v[8:9], v[8:9], 0, s[68:69]
	v_lshl_add_u64 v[8:9], v[8:9], 0, s[68:69]
	v_lshl_add_u64 v[8:9], v[8:9], 0, s[68:69]
	v_lshl_add_u64 v[8:9], v[8:9], 0, s[68:69]
	s_mov_b64 s[2:3], 0x3fffff
	v_cmp_lt_u64_e32 vcc, s[2:3], v[8:9]
	s_or_b64 s[4:5], vcc, s[4:5]
	s_waitcnt vmcnt(3)
	v_cvt_pk_bf16_f32 v4, v4, v5
	v_cvt_pk_bf16_f32 v5, v6, v7
	global_store_dwordx2 v[2:3], v[4:5], off
	v_lshl_add_u64 v[2:3], v[2:3], 0, s[10:11]
	s_waitcnt vmcnt(3)
	v_cvt_pk_bf16_f32 v12, v12, v13
	v_cvt_pk_bf16_f32 v13, v14, v15
	global_store_dwordx2 v[2:3], v[12:13], off
	v_lshl_add_u64 v[2:3], v[2:3], 0, s[10:11]
	s_waitcnt vmcnt(3)
	v_cvt_pk_bf16_f32 v16, v16, v17
	v_cvt_pk_bf16_f32 v17, v18, v19
	global_store_dwordx2 v[2:3], v[16:17], off
	v_lshl_add_u64 v[2:3], v[2:3], 0, s[10:11]
	s_waitcnt vmcnt(3)
	v_cvt_pk_bf16_f32 v20, v20, v21
	v_cvt_pk_bf16_f32 v21, v22, v23
	global_store_dwordx2 v[2:3], v[20:21], off
	v_lshl_add_u64 v[2:3], v[2:3], 0, s[10:11]
	s_andn2_b64 exec, exec, s[4:5]
	s_cbranch_execnz .Lpconv4
	s_branch .LBB0_733
